# MLA attention: conflict-free K LDS swizzle ((row>>1)&7) for ds_read_b128 lane groups
# speedup vs baseline: 1.0028x; 1.0028x over previous
; template <int MODE>
; __device__ __forceinline__ void attn_body(const Job J, char* lds) {
;     ...
;   const int tid = otid(), wid = tid >> 6, lane = tid & 63, r32 = lane & 31, hi = lane >> 5;
;   char* V_lds = lds; char* K_lds = lds + 2 * SHM_V;
;   float* wsf = (float*)(lds + 2 * SHM_V + 2 * SHM_K) + wid * 64; float* li_l = wsf; float* al_l = wsf + 32;
;   const float* tab = (const float*)(lds + 2 * SHM_V + 2 * SHM_K + NW * 256) + 64;
;   constexpr int NQR = (MODE == 2) ? 4 : 8;
;   float m_reg = -1e30f, l_reg = 0; f32x16 o[4] = {}; bf16x8 qr[NQR];
;   const bf16_t* Qw = J.Qb + (size_t)(wid * QBLK + r32) * J.ldq + hi * 8;
;   char* ql = lds + 2 * SHM_V + 2 * SHM_K + NW * 256 + (wid * 8 * 64 + lane) * 16;
; #pragma unroll
;   for (int d0 = 0; d0 < NQR; ++d0) qr[d0] = *reinterpret_cast<const bf16x8*>(Qw + d0 * 16);
;   if constexpr (MODE == 2) {
; #pragma unroll
;     for (int d0 = 4; d0 < 8; ++d0) *reinterpret_cast<bf16x8*>(ql + (d0 - 4) * 1024) = *reinterpret_cast<const bf16x8*>(Qw + d0 * 16);
;     const int tok = J.tok0 + wid * QBLK + r32; const int prow = tok >> 6, pcol = tok & 63;
; #pragma unroll
;     for (int ax = 0; ax < 2; ++ax) {
;       const float* cs = J.rope + (size_t)((ax == 0 ? prow : pcol) * 16 + hi * 8) * 2;
;       bf16x8 x1 = *reinterpret_cast<const bf16x8*>(Qw + (8 + 2 * ax) * 16), x2 = *reinterpret_cast<const bf16x8*>(Qw + (9 + 2 * ax) * 16); u32x4 w1, w2;
; #pragma unroll
;       for (int i = 0; i < 4; ++i) {
;         const f32x4 t = *(const f32x4*)(cs + 4 * i);
;         const float a0 = bf2f((bf16_t)x1[2 * i]), a1 = bf2f((bf16_t)x1[2 * i + 1]), b0 = bf2f((bf16_t)x2[2 * i]), b1 = bf2f((bf16_t)x2[2 * i + 1]);
;         w1[i] = cvt_pk_bf16(a0 * t[0] - b0 * t[1], a1 * t[2] - b1 * t[3]);
;         w2[i] = cvt_pk_bf16(a0 * t[1] + b0 * t[0], a1 * t[3] + b1 * t[2]);
;       }
;       *reinterpret_cast<u32x4*>(ql + (4 + 2 * ax) * 1024) = w1; *reinterpret_cast<u32x4*>(ql + (5 + 2 * ax) * 1024) = w2;
;     }
;   }
;   const int sr = tid >> 4, sc = (tid & 15) * 8, vst0 = v_st(sr, sc), vst1 = v_st(32 + sr, sc);
;   const int pr = tid >> 3, pc = (tid & 7) * 8;
;   const int vb0 = (int)(uintptr_t)V_lds + v_rd_base(lane);
;   bf16x8 vs0, vs1, ks0, ks1, kp;
;   const int rq = J.qb4 + (wid >> 1), qc = (wid & 1) * 32 + r32;
;   const int rs = min(max(rq - 4, 0), 24), cs_ = min(max(qc - 8, 0), 48);
.LBB0_1392:
	s_bfe_u32 s72, s71, 0x30003
	s_bfe_u32 s6, s71, 0x20006
	s_lshl_b32 s6, s6, 3
	s_or_b32 s72, s72, s6
	s_and_b32 s6, s71, 7
	s_lshl_b32 s6, s6, 5
	s_or_b32 s72, s72, s6
	s_and_b32 s6, s71, 0x300
	s_or_b32 s72, s72, s6
	s_ashr_i32 s6, s72, 7
	s_lshl_b32 s7, s72, 8
	s_lshl_b32 s73, s6, 11
	s_and_b32 s7, s7, 0x700
	s_or_b32 s36, s73, s7
	s_bfe_u32 s72, s72, 0x40003
	s_ashr_i32 s37, s36, 31
	s_mul_i32 s9, s36, 0x1800
	s_mul_hi_i32 s8, s36, 0x1800
	s_add_u32 s9, s0, s9
	v_mov_b32_e32 v119, v170
	s_barrier
	s_addc_u32 s38, s1, s8
	s_mul_i32 s8, s72, 0x180
	s_add_u32 s8, s9, s8
	v_ashrrev_i32_e32 v32, 6, v119
	v_and_b32_e32 v138, 31, v119
	v_lshlrev_b32_e32 v118, 5, v32
	v_or_b32_e32 v16, s7, v138
	s_addc_u32 s9, s38, 0
	v_bfe_u32 v137, v119, 5, 1
	v_add_u32_e32 v34, v16, v118
	v_or_b32_e32 v2, v118, v138
	v_mov_b64_e32 v[0:1], s[8:9]
	v_lshlrev_b32_e32 v33, 3, v137
	v_ashrrev_i32_e32 v16, 2, v34
	v_mad_i64_i32 v[0:1], s[8:9], v2, s40, v[0:1]
	v_lshlrev_b32_e32 v116, 4, v137
	v_and_or_b32 v24, v16, -16, v33
	v_lshl_add_u64 v[28:29], v[0:1], 0, v[116:117]
	v_ashrrev_i32_e32 v25, 31, v24
	global_load_dwordx4 v[0:3], v[28:29], off offset:128
	global_load_dwordx4 v[4:7], v[28:29], off offset:160
	global_load_dwordx4 v[8:11], v[28:29], off offset:192
	global_load_dwordx4 v[12:15], v[28:29], off offset:224
	global_load_dwordx4 v[16:19], v[28:29], off offset:256
	global_load_dwordx4 v[20:23], v[28:29], off offset:288
	v_lshl_add_u64 v[30:31], v[24:25], 3, s[30:31]
	global_load_dwordx4 v[24:27], v[30:31], off
	v_and_b32_e32 v120, 63, v119
	v_lshl_add_u32 v32, v32, 13, s43
	v_lshlrev_b32_e32 v121, 4, v120
	v_add_u32_e32 v142, v32, v121
	global_load_dwordx4 v[108:111], v[28:29], off
	global_load_dwordx4 v[104:107], v[28:29], off offset:32
	global_load_dwordx4 v[100:103], v[28:29], off offset:64
	global_load_dwordx4 v[96:99], v[28:29], off offset:96
	v_ashrrev_i32_e32 v144, 3, v119
	v_ashrrev_i32_e32 v143, 4, v119
	s_lshl_b32 s7, s72, 9
	v_add_u32_e32 v145, 32, v143
	s_add_u32 s8, s2, s7
	v_mov_b32_e32 v115, v117
	s_addc_u32 s9, s3, 0
	v_mov_b32_e32 v113, v117
	v_lshlrev_b32_e32 v32, 1, v143
	v_mul_lo_u32 v35, v143, s41
	v_lshlrev_b32_e32 v37, 3, v144
	v_mul_lo_u32 v36, v144, s41
	v_mad_u32_u24 v122, v138, s41, 0
	v_add_u32_e32 v35, 0, v35
	v_and_b32_e32 v37, 0x70, v37
	v_add_u32_e32 v36, 0, v36
	v_add_u32_e32 v38, 0x3000, v35
	s_lshl_b32 s74, s6, 8
	s_addk_i32 s74, 0x4000
	s_cmp_lg_u32 0, -1
	s_cselect_b32 s38, 0, 0
	v_and_b32_e32 v123, 0x3fffffc0, v119
	v_lshlrev_b32_e32 v125, 1, v119
	v_and_b32_e32 v126, 0xc0, v121
	v_add_u32_e32 v178, 0xe000, v122
	v_and_b32_e32 v125, 32, v125
	s_mov_b32 s75, 2
	s_waitcnt vmcnt(10)
	ds_write_b128 v142, v[0:3]
	s_waitcnt vmcnt(9)
	ds_write_b128 v142, v[4:7] offset:1024
	s_waitcnt vmcnt(8)
	ds_write_b128 v142, v[8:11] offset:2048
	s_waitcnt vmcnt(7)
	ds_write_b128 v142, v[12:15] offset:3072
	s_waitcnt vmcnt(6)
	v_lshlrev_b32_e32 v1, 16, v16
	s_waitcnt vmcnt(5)
	v_lshlrev_b32_e32 v0, 16, v20
	v_and_b32_e32 v3, 0xffff0000, v16
	v_and_b32_e32 v2, 0xffff0000, v20
	s_waitcnt vmcnt(4)
	v_pk_mul_f32 v[4:5], v[24:25], v[0:1] op_sel:[0,1] op_sel_hi:[1,0]
	v_pk_mul_f32 v[0:1], v[24:25], v[0:1]
	v_pk_mul_f32 v[6:7], v[26:27], v[2:3] op_sel:[0,1] op_sel_hi:[1,0]
	v_pk_mul_f32 v[2:3], v[26:27], v[2:3]
	v_sub_f32_e32 v4, v4, v5
	v_add_f32_e32 v1, v1, v0
	v_sub_f32_e32 v0, v6, v7
	v_add_f32_e32 v2, v3, v2
	v_cvt_pk_bf16_f32 v0, v4, v0
	v_cvt_pk_bf16_f32 v4, v1, v2
	global_load_dwordx4 v[6:9], v[30:31], off offset:16
	v_lshlrev_b32_e32 v3, 16, v17
	v_lshlrev_b32_e32 v2, 16, v21
	v_and_b32_e32 v11, 0xffff0000, v17
	v_and_b32_e32 v10, 0xffff0000, v21
	v_and_b32_e32 v15, 0xffff0000, v19
	v_and_b32_e32 v14, 0xffff0000, v23
	s_waitcnt vmcnt(0)
	v_pk_mul_f32 v[12:13], v[6:7], v[2:3] op_sel:[0,1] op_sel_hi:[1,0]
	v_pk_mul_f32 v[2:3], v[6:7], v[2:3]
	v_pk_mul_f32 v[6:7], v[8:9], v[10:11] op_sel:[0,1] op_sel_hi:[1,0]
	v_pk_mul_f32 v[8:9], v[8:9], v[10:11]
	v_sub_f32_e32 v1, v12, v13
	v_add_f32_e32 v5, v9, v8
	v_add_f32_e32 v2, v3, v2
	v_sub_f32_e32 v3, v6, v7
	v_cvt_pk_bf16_f32 v1, v1, v3
	v_cvt_pk_bf16_f32 v5, v2, v5
	global_load_dwordx4 v[6:9], v[30:31], off offset:32
	v_lshlrev_b32_e32 v3, 16, v18
	v_lshlrev_b32_e32 v2, 16, v22
	v_and_b32_e32 v11, 0xffff0000, v18
	v_and_b32_e32 v10, 0xffff0000, v22
	v_lshlrev_b32_e32 v18, 4, v34
	v_and_b32_e32 v34, 3, v143
	s_waitcnt vmcnt(0)
	v_pk_mul_f32 v[12:13], v[6:7], v[2:3] op_sel:[0,1] op_sel_hi:[1,0]
	v_pk_mul_f32 v[2:3], v[6:7], v[2:3]
	v_pk_mul_f32 v[6:7], v[8:9], v[10:11] op_sel:[0,1] op_sel_hi:[1,0]
	v_pk_mul_f32 v[8:9], v[8:9], v[10:11]
	v_sub_f32_e32 v10, v12, v13
	v_add_f32_e32 v3, v3, v2
	v_sub_f32_e32 v2, v6, v7
	v_add_f32_e32 v6, v9, v8
	v_cvt_pk_bf16_f32 v2, v10, v2
	v_cvt_pk_bf16_f32 v6, v3, v6
	global_load_dwordx4 v[8:11], v[30:31], off offset:48
	v_lshlrev_b32_e32 v13, 16, v19
	v_lshlrev_b32_e32 v12, 16, v23
	v_lshlrev_b32_e32 v30, 3, v119
	v_lshlrev_b32_e32 v31, 4, v119
	v_and_b32_e32 v114, 0x70, v31
	v_bitop3_b32 v146, v116, v30, s47 bitop3:0x78
	v_bitop3_b32 v37, v114, v37, s46 bitop3:0x36
	v_and_b32_e32 v31, 0x70, v30
	v_add_u32_e32 v147, v122, v146
	v_add_u32_e32 v150, v36, v37
	v_bitop3_b32 v158, v116, v31, 32 bitop3:0x36
	v_add_u32_e32 v153, v122, v158
	v_bitop3_b32 v161, v116, v31, 64 bitop3:0x36
	v_add_u32_e32 v154, v122, v161
	v_bitop3_b32 v164, v116, v31, s49 bitop3:0x36
	v_add_u32_e32 v155, v122, v164
	v_bitop3_b32 v167, v116, v31, s50 bitop3:0x36
	v_add_u32_e32 v156, v122, v167
	v_bitop3_b32 v169, v116, v31, s51 bitop3:0x36
	v_add_u32_e32 v160, v122, v169
	v_bitop3_b32 v172, v116, v31, s45 bitop3:0x36
	v_add_u32_e32 v159, v122, v172
	v_bitop3_b32 v173, v116, v31, s52 bitop3:0x36
	v_add_u32_e32 v162, v122, v173
	v_bitop3_b32 v174, v116, v31, s46 bitop3:0x36
	v_add_u32_e32 v163, v122, v174
	v_bitop3_b32 v175, v116, v31, s53 bitop3:0x36
	v_add_u32_e32 v166, v122, v175
	v_bitop3_b32 v176, v116, v31, s54 bitop3:0x36
	v_add_u32_e32 v165, v122, v176
	v_bitop3_b32 v177, v116, v31, s55 bitop3:0x36
	v_add_u32_e32 v168, v122, v177
	s_waitcnt vmcnt(0)
; __device__ __forceinline__ unsigned cvt_pk_bf16(float lo, float hi) { unsigned r; asm volatile("v_cvt_pk_bf16_f32 %0, %1, %2" : "=v"(r) : "v"(lo), "v"(hi)); return r; }
; __device__ __forceinline__ float bf2f(bf16_t b) { return __uint_as_float(((unsigned)b) << 16); }
; __device__ __forceinline__ int v_st(int k, int c) { const int kk = (k & ~0xC) | ((k & 4) << 1) | ((k & 8) >> 1); return ((kk >> 3) * 4 + (c >> 5)) * 512 + ((kk & 7) * 32 + (c & 31)) * 2; }
; __device__ __forceinline__ int v_rd_base(int lane) { return ((lane & 3) << 3) | (((lane >> 2) & 3) << 6) | (((lane >> 4) & 1) << 5) | (((lane >> 5) & 1) << 8); }
; #define SWAIT() asm volatile("s_waitcnt vmcnt(0)" ::: "memory")
; template <int MODE>
; __device__ __forceinline__ void attn_body(const Job J, char* lds) {
;     ...
;       bf16x8 x1 = *reinterpret_cast<const bf16x8*>(Qw + (8 + 2 * ax) * 16), x2 = *reinterpret_cast<const bf16x8*>(Qw + (9 + 2 * ax) * 16); u32x4 w1, w2;
; #pragma unroll
;       for (int i = 0; i < 4; ++i) {
;         const f32x4 t = *(const f32x4*)(cs + 4 * i);
;         const float a0 = bf2f((bf16_t)x1[2 * i]), a1 = bf2f((bf16_t)x1[2 * i + 1]), b0 = bf2f((bf16_t)x2[2 * i]), b1 = bf2f((bf16_t)x2[2 * i + 1]);
;         w1[i] = cvt_pk_bf16(a0 * t[0] - b0 * t[1], a1 * t[2] - b1 * t[3]);
;         w2[i] = cvt_pk_bf16(a0 * t[1] + b0 * t[0], a1 * t[3] + b1 * t[2]);
;       }
;       *reinterpret_cast<u32x4*>(ql + (4 + 2 * ax) * 1024) = w1; *reinterpret_cast<u32x4*>(ql + (5 + 2 * ax) * 1024) = w2;
;     }
;   }
;   const int sr = tid >> 4, sc = (tid & 15) * 8, vst0 = v_st(sr, sc), vst1 = v_st(32 + sr, sc);
;   const int pr = tid >> 3, pc = (tid & 7) * 8;
;   const int vb0 = (int)(uintptr_t)V_lds + v_rd_base(lane);
;   bf16x8 vs0, vs1, ks0, ks1, kp;
;   const int rq = J.qb4 + (wid >> 1), qc = (wid & 1) * 32 + r32;
;   const int rs = min(max(rq - 4, 0), 24), cs_ = min(max(qc - 8, 0), 48);
;     ...
;   SLOAD(0); SWAIT(); SWRITE(0); __syncthreads();
	v_pk_mul_f32 v[16:17], v[8:9], v[12:13] op_sel:[0,1] op_sel_hi:[1,0]
	v_pk_mul_f32 v[8:9], v[8:9], v[12:13]
	v_pk_mul_f32 v[12:13], v[10:11], v[14:15] op_sel:[0,1] op_sel_hi:[1,0]
	v_pk_mul_f32 v[10:11], v[10:11], v[14:15]
	v_sub_f32_e32 v3, v16, v17
	v_add_f32_e32 v7, v9, v8
	v_sub_f32_e32 v8, v12, v13
	v_add_f32_e32 v9, v11, v10
	v_and_or_b32 v16, v18, s44, v33
	v_cvt_pk_bf16_f32 v3, v3, v8
	v_cvt_pk_bf16_f32 v7, v7, v9
	global_load_dwordx4 v[8:11], v[28:29], off offset:320
	global_load_dwordx4 v[12:15], v[28:29], off offset:352
	v_lshlrev_b32_e32 v20, 3, v16
	global_load_dwordx4 v[16:19], v20, s[30:31]
	ds_write_b128 v142, v[0:3] offset:4096
	ds_write_b128 v142, v[4:7] offset:5120
	v_lshrrev_b32_e32 v33, 1, v143
	s_waitcnt vmcnt(2)
	v_lshlrev_b32_e32 v1, 16, v8
	s_waitcnt vmcnt(1)
	v_lshlrev_b32_e32 v0, 16, v12
	v_and_b32_e32 v3, 0xffff0000, v8
	v_and_b32_e32 v2, 0xffff0000, v12
	s_waitcnt vmcnt(0)
	v_pk_mul_f32 v[4:5], v[16:17], v[0:1] op_sel:[0,1] op_sel_hi:[1,0]
	v_pk_mul_f32 v[0:1], v[16:17], v[0:1]
	v_pk_mul_f32 v[6:7], v[18:19], v[2:3] op_sel:[0,1] op_sel_hi:[1,0]
	v_pk_mul_f32 v[2:3], v[18:19], v[2:3]
	v_sub_f32_e32 v4, v4, v5
	v_add_f32_e32 v0, v1, v0
	v_sub_f32_e32 v1, v6, v7
	v_add_f32_e32 v2, v3, v2
	v_cvt_pk_bf16_f32 v4, v4, v1
	v_cvt_pk_bf16_f32 v0, v0, v2
	global_load_dwordx4 v[16:19], v20, s[30:31] offset:16
	v_lshlrev_b32_e32 v3, 16, v9
	v_lshlrev_b32_e32 v2, 16, v13
	v_and_b32_e32 v7, 0xffff0000, v9
	v_and_b32_e32 v6, 0xffff0000, v13
	s_waitcnt vmcnt(0)
	v_pk_mul_f32 v[8:9], v[16:17], v[2:3] op_sel:[0,1] op_sel_hi:[1,0]
	v_pk_mul_f32 v[12:13], v[18:19], v[6:7] op_sel:[0,1] op_sel_hi:[1,0]
	v_pk_mul_f32 v[6:7], v[18:19], v[6:7]
	v_pk_mul_f32 v[2:3], v[16:17], v[2:3]
	v_sub_f32_e32 v1, v8, v9
	v_add_f32_e32 v6, v7, v6
	v_add_f32_e32 v2, v3, v2
	v_sub_f32_e32 v3, v12, v13
	v_cvt_pk_bf16_f32 v5, v1, v3
	v_cvt_pk_bf16_f32 v1, v2, v6
	global_load_dwordx4 v[6:9], v20, s[30:31] offset:32
	v_lshlrev_b32_e32 v3, 16, v10
	v_lshlrev_b32_e32 v2, 16, v14
	v_and_b32_e32 v13, 0xffff0000, v10
	v_and_b32_e32 v12, 0xffff0000, v14
	s_waitcnt vmcnt(0)
	v_pk_mul_f32 v[16:17], v[6:7], v[2:3] op_sel:[0,1] op_sel_hi:[1,0]
	v_pk_mul_f32 v[2:3], v[6:7], v[2:3]
	v_pk_mul_f32 v[6:7], v[8:9], v[12:13] op_sel:[0,1] op_sel_hi:[1,0]
	v_pk_mul_f32 v[8:9], v[8:9], v[12:13]
	v_add_f32_e32 v2, v3, v2
	v_sub_f32_e32 v10, v16, v17
	v_sub_f32_e32 v3, v6, v7
	v_add_f32_e32 v7, v9, v8
	v_cvt_pk_bf16_f32 v6, v10, v3
	v_cvt_pk_bf16_f32 v2, v2, v7
	global_load_dwordx4 v[16:19], v20, s[30:31] offset:48
	v_add_u32_e32 v12, s73, v144
	v_add_u32_e32 v8, s73, v143
	v_ashrrev_i32_e32 v13, 31, v12
	v_ashrrev_i32_e32 v9, 31, v8
	v_lshlrev_b64 v[12:13], 7, v[12:13]
	v_and_b32_e32 v3, 0x78, v30
	v_add_u32_e32 v20, s73, v145
	v_lshlrev_b64 v[22:23], 13, v[8:9]
	v_lshl_add_u64 v[12:13], s[10:11], 0, v[12:13]
	v_lshlrev_b32_e32 v112, 1, v3
	v_ashrrev_i32_e32 v21, 31, v20
	v_lshl_add_u64 v[26:27], v[12:13], 0, v[114:115]
	v_lshl_add_u64 v[12:13], s[8:9], 0, v[22:23]
	v_lshlrev_b64 v[20:21], 13, v[20:21]
	v_lshl_add_u64 v[22:23], v[12:13], 0, v[112:113]
	v_lshlrev_b32_e32 v13, 16, v11
	v_lshlrev_b32_e32 v12, 16, v15
	v_and_b32_e32 v11, 0xffff0000, v11
	v_and_b32_e32 v10, 0xffff0000, v15
	v_lshl_add_u64 v[20:21], s[8:9], 0, v[20:21]
	v_lshl_add_u64 v[24:25], v[20:21], 0, v[112:113]
	v_bfe_u32 v30, v30, 5, 2
	s_waitcnt vmcnt(0)
	v_pk_mul_f32 v[14:15], v[16:17], v[12:13] op_sel:[0,1] op_sel_hi:[1,0]
	v_pk_mul_f32 v[12:13], v[16:17], v[12:13]
	v_pk_mul_f32 v[16:17], v[18:19], v[10:11] op_sel:[0,1] op_sel_hi:[1,0]
	v_pk_mul_f32 v[10:11], v[18:19], v[10:11]
	v_sub_f32_e32 v3, v14, v15
	v_sub_f32_e32 v7, v16, v17
	v_add_f32_e32 v10, v11, v10
	v_add_f32_e32 v9, v13, v12
	v_cvt_pk_bf16_f32 v7, v3, v7
	v_cvt_pk_bf16_f32 v3, v9, v10
	global_load_dwordx4 v[10:13], v[22:23], off offset:256
	global_load_dwordx4 v[14:17], v[24:25], off offset:256
	global_load_dwordx4 v[18:21], v[22:23], off
	s_nop 0
	global_load_dwordx4 v[22:25], v[24:25], off
	s_nop 0
	global_load_dwordx4 v[26:29], v[26:27], off
	v_and_b32_e32 v9, 0xfffff0, v143
	v_and_or_b32 v9, v32, 8, v9
	v_and_or_b32 v32, v33, 4, v34
	v_and_b32_e32 v33, 0xfffff0, v145
	v_lshlrev_b32_e32 v34, 1, v145
	v_lshrrev_b32_e32 v9, 1, v9
	v_and_or_b32 v33, v34, 8, v33
	v_or_b32_e32 v9, v9, v30
	v_lshrrev_b32_e32 v33, 1, v33
	v_lshlrev_b32_e32 v31, 6, v32
	v_and_b32_e32 v32, 48, v112
	v_lshlrev_b32_e32 v9, 9, v9
	v_or_b32_e32 v30, v33, v30
	v_or3_b32 v9, v9, v31, v32
	v_lshlrev_b32_e32 v30, 9, v30
	v_lshrrev_b32_e32 v34, 1, v119
	v_bitop3_b32 v34, v112, v34, s47 bitop3:0x78
	v_or3_b32 v30, v30, v31, v32
	v_add_u32_e32 v151, 0, v9
	ds_write_b128 v142, v[4:7] offset:6144
	ds_write_b128 v142, v[0:3] offset:7168
	v_add_u32_e32 v148, v35, v34
	v_add_u32_e32 v149, v38, v34
	v_add_u32_e32 v152, 0, v30
	s_waitcnt vmcnt(0)
	s_waitcnt vmcnt(4)
	ds_write_b128 v151, v[10:13]
	s_waitcnt vmcnt(3)
	ds_write_b128 v152, v[14:17]
	s_waitcnt vmcnt(2)
	ds_write_b128 v148, v[18:21] offset:32768
	s_waitcnt vmcnt(1)
	ds_write_b128 v149, v[22:25] offset:32768
	s_waitcnt vmcnt(0)
	ds_write_b128 v150, v[26:29] offset:32768
	s_waitcnt lgkmcnt(0)
	s_barrier
; #define SWAIT() asm volatile("s_waitcnt vmcnt(0)" ::: "memory")
; template <int DQK>
; __device__ __forceinline__ void qkt(f32x16& p0, f32x16& p1, const char* Ks, const bf16x8* qr, const char* ql, int r32, int hi) {
;   p0 = f32x16{}; p1 = f32x16{};
; #pragma unroll
;   for (int d0 = 0; d0 < DQK / 16; ++d0) { const int cb = (d0 * 16 + hi * 8) * 2;
;     bf16x8 b0 = *reinterpret_cast<const bf16x8*>(Ks + r32 * (DQK * 2) + (cb ^ ((r32 & 7) << 4)));
;     bf16x8 b1 = *reinterpret_cast<const bf16x8*>(Ks + (32 + r32) * (DQK * 2) + (cb ^ ((r32 & 7) << 4)));
;     constexpr int NQR = DQK == 192 ? 4 : 8;
;     bf16x8 qv; if (d0 < NQR) qv = qr[d0 < NQR ? d0 : 0]; else qv = *reinterpret_cast<const bf16x8*>(ql + (d0 - NQR) * 1024);
;     p0 = __builtin_amdgcn_mfma_f32_32x32x16_bf16(b0, qv, p0, 0, 0, 0);
;     p1 = __builtin_amdgcn_mfma_f32_32x32x16_bf16(b1, qv, p1, 0, 0, 0); }
; template <int MODE>
; __device__ __forceinline__ void attn_body(const Job J, char* lds) {
;     ...
;   SLOAD(0); SWAIT(); SWRITE(0); __syncthreads();
;   qkt<DQK>(pA0, pA1, K_lds, qr, ql, r32, hi); MASK(pA0, pA1, 0); partialSM(pA0, pA1, m_reg, mnA, alA, C, THRS);
;   SLOAD(1);
	ds_read_b128 v[0:3], v147 offset:32768
	ds_read_b128 v[4:7], v147 offset:45056
	s_waitcnt lgkmcnt(1)
	v_mfma_f32_32x32x16_bf16 v[64:79], v[0:3], v[108:111], 0
	v_lshl_add_u32 v119, v123, 2, s42
	v_lshlrev_b32_e32 v123, 3, v120
	v_and_b32_e32 v127, 0x100, v123
	v_lshl_add_u32 v139, v138, 2, v119
	s_waitcnt lgkmcnt(0)
	v_mfma_f32_32x32x16_bf16 v[80:95], v[4:7], v[108:111], 0
	ds_read_b128 v[0:3], v153 offset:32768
	ds_read_b128 v[4:7], v153 offset:45056
	s_waitcnt lgkmcnt(1)
	v_mfma_f32_32x32x16_bf16 v[64:79], v[0:3], v[104:107], v[64:79]
	s_waitcnt lgkmcnt(0)
	v_mfma_f32_32x32x16_bf16 v[80:95], v[4:7], v[104:107], v[80:95]
	ds_read_b128 v[0:3], v154 offset:32768
	ds_read_b128 v[4:7], v154 offset:45056
	s_waitcnt lgkmcnt(1)
	v_mfma_f32_32x32x16_bf16 v[64:79], v[0:3], v[100:103], v[64:79]
	s_waitcnt lgkmcnt(0)
	v_mfma_f32_32x32x16_bf16 v[80:95], v[4:7], v[100:103], v[80:95]
	ds_read_b128 v[0:3], v155 offset:32768
	ds_read_b128 v[4:7], v155 offset:45056
	s_waitcnt lgkmcnt(1)
	v_mfma_f32_32x32x16_bf16 v[64:79], v[0:3], v[96:99], v[64:79]
	s_waitcnt lgkmcnt(0)
	v_mfma_f32_32x32x16_bf16 v[80:95], v[4:7], v[96:99], v[80:95]
	ds_read_b128 v[0:3], v156 offset:32768
	ds_read_b128 v[4:7], v142
	ds_read_b128 v[10:13], v156 offset:45056
	ds_read_b128 v[14:17], v142 offset:1024
	s_waitcnt lgkmcnt(2)
	v_mfma_f32_32x32x16_bf16 v[64:79], v[0:3], v[4:7], v[64:79]
	s_waitcnt lgkmcnt(1)
	v_mfma_f32_32x32x16_bf16 v[80:95], v[10:13], v[4:7], v[80:95]
	ds_read_b128 v[0:3], v160 offset:32768
	ds_read_b128 v[4:7], v160 offset:45056
	s_waitcnt lgkmcnt(1)
	v_mfma_f32_32x32x16_bf16 v[64:79], v[0:3], v[14:17], v[64:79]
	s_waitcnt lgkmcnt(0)
	v_mfma_f32_32x32x16_bf16 v[80:95], v[4:7], v[14:17], v[80:95]
	ds_read_b128 v[0:3], v159 offset:32768
	ds_read_b128 v[4:7], v142 offset:2048
	ds_read_b128 v[10:13], v159 offset:45056
	ds_read_b128 v[14:17], v142 offset:3072
	s_waitcnt lgkmcnt(2)
	v_mfma_f32_32x32x16_bf16 v[64:79], v[0:3], v[4:7], v[64:79]
	s_waitcnt lgkmcnt(1)
	v_mfma_f32_32x32x16_bf16 v[80:95], v[10:13], v[4:7], v[80:95]
	ds_read_b128 v[0:3], v162 offset:32768
	ds_read_b128 v[4:7], v162 offset:45056
	s_waitcnt lgkmcnt(1)
	v_mfma_f32_32x32x16_bf16 v[64:79], v[0:3], v[14:17], v[64:79]
	s_waitcnt lgkmcnt(0)
	v_mfma_f32_32x32x16_bf16 v[80:95], v[4:7], v[14:17], v[80:95]
	ds_read_b128 v[0:3], v163 offset:32768
	ds_read_b128 v[4:7], v142 offset:4096
	ds_read_b128 v[10:13], v163 offset:45056
	ds_read_b128 v[14:17], v142 offset:5120
	s_waitcnt lgkmcnt(2)
	v_mfma_f32_32x32x16_bf16 v[64:79], v[0:3], v[4:7], v[64:79]
	s_waitcnt lgkmcnt(1)
	v_mfma_f32_32x32x16_bf16 v[80:95], v[10:13], v[4:7], v[80:95]
	ds_read_b128 v[0:3], v166 offset:32768
	ds_read_b128 v[4:7], v166 offset:45056
	s_waitcnt lgkmcnt(1)
	v_mfma_f32_32x32x16_bf16 v[64:79], v[0:3], v[14:17], v[64:79]
	s_waitcnt lgkmcnt(0)
	v_mfma_f32_32x32x16_bf16 v[80:95], v[4:7], v[14:17], v[80:95]
	ds_read_b128 v[0:3], v165 offset:32768
	ds_read_b128 v[4:7], v142 offset:6144
	ds_read_b128 v[10:13], v165 offset:45056
	ds_read_b128 v[14:17], v142 offset:7168
	s_waitcnt lgkmcnt(2)
	v_mfma_f32_32x32x16_bf16 v[64:79], v[0:3], v[4:7], v[64:79]
	ds_read_b128 v[0:3], v168 offset:32768
	s_waitcnt lgkmcnt(2)
	v_mfma_f32_32x32x16_bf16 v[80:95], v[10:13], v[4:7], v[80:95]
	v_add_u32_e32 v4, 0x60, v8
	v_ashrrev_i32_e32 v5, 31, v4
	v_lshlrev_b64 v[8:9], 13, v[4:5]
	ds_read_b128 v[4:7], v168 offset:45056
	s_waitcnt lgkmcnt(1)
	v_mfma_f32_32x32x16_bf16 v[64:79], v[0:3], v[14:17], v[64:79]
	v_lshl_add_u64 v[0:1], s[8:9], 0, v[8:9]
	v_lshl_add_u64 v[0:1], v[0:1], 0, v[112:113]
	global_load_dwordx4 v[180:183], v[0:1], off offset:256
	global_load_dwordx4 v[186:189], v[0:1], off
	s_waitcnt lgkmcnt(0)
; #define SWAIT() asm volatile("s_waitcnt vmcnt(0)" ::: "memory")
; __device__ __forceinline__ void partialSM(f32x16& p0, f32x16& p1, float& m_reg, float& mn, float& alpha, const float C, const float THRS) {
;   float pmax = p0[0];
; #pragma unroll
;   for (int r = 1; r < 16; ++r) pmax = fmaxf(pmax, p0[r]);
; #pragma unroll
;   for (int r = 0; r < 16; ++r) pmax = fmaxf(pmax, p1[r]);
;   { auto rr = __builtin_amdgcn_permlane32_swap(__float_as_uint(pmax), __float_as_uint(pmax), false, false);
;     pmax = fmaxf(__uint_as_float(rr[0]), __uint_as_float(rr[1])); }
;   if (__builtin_expect(__all(pmax - m_reg <= THRS), 1)) { mn = m_reg; alpha = 1.f; }
;   else { mn = fmaxf(m_reg, pmax); alpha = __builtin_amdgcn_exp2f((m_reg - mn) * C); m_reg = mn; }
;   float mnC = -mn * C;
; #pragma unroll
;   for (int r = 0; r < 16; ++r) p0[r] = fmaf(p0[r], C, mnC);
; #pragma unroll
;   for (int r = 0; r < 16; ++r) p1[r] = fmaf(p1[r], C, mnC);
; #pragma unroll
;   for (int r = 0; r < 16; ++r) p0[r] = __builtin_amdgcn_exp2f(p0[r]);
; }
; template <int MODE>
; __device__ __forceinline__ void attn_body(const Job J, char* lds) {
;     ...
;   SLOAD(1);
;   SWAIT(); SWRITE(1); __syncthreads();
	v_mfma_f32_32x32x16_bf16 v[80:95], v[4:7], v[14:17], v[80:95]
	s_nop 5
	v_max_f32_e32 v0, v65, v65
	v_max_f32_e32 v1, v64, v64
	v_max_f32_e32 v0, v1, v0
	v_max3_f32 v0, v0, v66, v67
	v_max3_f32 v0, v0, v68, v69
	v_max3_f32 v0, v0, v70, v71
	v_max3_f32 v0, v0, v72, v73
	v_max3_f32 v0, v0, v74, v75
	v_max3_f32 v0, v0, v76, v77
	v_max3_f32 v0, v0, v78, v79
	v_max3_f32 v0, v0, v80, v81
	v_max3_f32 v0, v0, v82, v83
	v_max3_f32 v0, v0, v84, v85
	v_max3_f32 v0, v0, v86, v87
	v_max3_f32 v0, v0, v88, v89
	v_max3_f32 v0, v0, v90, v91
	v_max3_f32 v0, v0, v92, v93
	v_max3_f32 v0, v0, v94, v95
	v_mov_b32_e32 v1, v0
	s_nop 1
	v_permlane32_swap_b32_e32 v0, v1
	v_max_f32_e32 v1, v1, v1
	v_max_f32_e32 v0, v0, v0
	v_max_f32_e32 v0, v0, v1
	v_add_f32_e32 v1, 0x7149f2ca, v0
	v_cmp_ge_f32_e32 vcc, s56, v1
	s_cmp_eq_u64 vcc, exec
	s_cselect_b64 vcc, -1, 0
	s_or_b32 s6, s73, 64
	v_max_f32_e32 v124, 0xf149f2ca, v0
	v_add_u32_e32 v0, s6, v143
	v_ashrrev_i32_e32 v1, 31, v0
	v_lshlrev_b64 v[0:1], 13, v[0:1]
	v_lshl_add_u64 v[0:1], s[8:9], 0, v[0:1]
	v_add_u32_e32 v2, s6, v144
	v_lshl_add_u64 v[0:1], v[0:1], 0, v[112:113]
	v_ashrrev_i32_e32 v3, 31, v2
	global_load_dwordx4 v[190:193], v[0:1], off offset:256
	global_load_dwordx4 v[214:217], v[0:1], off
	v_lshlrev_b64 v[2:3], 7, v[2:3]
	v_lshl_add_u64 v[2:3], s[10:11], 0, v[2:3]
	v_lshl_add_u64 v[0:1], v[2:3], 0, v[114:115]
	global_load_dwordx4 v[218:221], v[0:1], off
	v_cndmask_b32_e32 v184, v124, v136, vcc
	v_cmp_gt_u32_e64 s[6:7], 32, v120
	v_lshl_add_u64 v[120:121], s[10:11], 0, v[114:115]
	v_and_or_b32 v114, v123, 24, v126
	v_lshl_add_u64 v[122:123], s[8:9], 0, v[112:113]
	v_sub_f32_e32 v112, 0xf149f2ca, v124
	v_mul_f32_e32 v130, 0xbdd53b94, v184
	v_mul_f32_e32 v112, 0x3dd53b94, v112
	v_mov_b32_e32 v185, v130
	v_exp_f32_e32 v141, v112
	v_fmamk_f32 v64, v64, 0x3dd53b94, v130
	v_fmamk_f32 v65, v65, 0x3dd53b94, v130
	v_fmamk_f32 v66, v66, 0x3dd53b94, v130
	v_fmamk_f32 v67, v67, 0x3dd53b94, v130
	v_fmamk_f32 v68, v68, 0x3dd53b94, v130
	v_fmamk_f32 v69, v69, 0x3dd53b94, v130
	v_fmamk_f32 v70, v70, 0x3dd53b94, v130
	v_fmamk_f32 v71, v71, 0x3dd53b94, v130
	v_fmamk_f32 v72, v72, 0x3dd53b94, v130
	v_fmamk_f32 v73, v73, 0x3dd53b94, v130
	v_fmamk_f32 v74, v74, 0x3dd53b94, v130
	v_fmamk_f32 v75, v75, 0x3dd53b94, v130
	v_fmamk_f32 v76, v76, 0x3dd53b94, v130
	v_fmamk_f32 v77, v77, 0x3dd53b94, v130
	v_fmamk_f32 v78, v78, 0x3dd53b94, v130
	v_fmac_f32_e32 v185, 0x3dd53b94, v79
	v_mov_b64_e32 v[0:1], s[12:13]
	v_exp_f32_e32 v210, v64
	v_exp_f32_e32 v212, v65
	v_exp_f32_e32 v208, v66
	v_exp_f32_e32 v211, v67
	v_exp_f32_e32 v207, v68
	v_exp_f32_e32 v209, v69
	v_exp_f32_e32 v205, v70
	v_exp_f32_e32 v206, v71
	v_exp_f32_e32 v202, v72
	v_exp_f32_e32 v204, v73
	v_exp_f32_e32 v201, v74
	v_exp_f32_e32 v203, v75
	v_exp_f32_e32 v198, v76
	v_exp_f32_e32 v200, v77
	v_exp_f32_e32 v197, v78
	v_exp_f32_e32 v199, v185
	v_mov_b64_e32 v[14:15], s[26:27]
	v_or3_b32 v114, v114, v125, v127
	s_waitcnt vmcnt(0)
	v_mov_b64_e32 v[2:3], s[14:15]
	v_mov_b64_e32 v[4:5], s[16:17]
	v_mov_b64_e32 v[6:7], s[18:19]
	v_mov_b64_e32 v[8:9], s[20:21]
	v_mov_b64_e32 v[10:11], s[22:23]
	v_mov_b64_e32 v[12:13], s[24:25]
	v_mov_b64_e32 v[62:63], v[14:15]
	v_mov_b64_e32 v[46:47], v[14:15]
	v_mov_b64_e32 v[30:31], v[14:15]
	v_add_u32_e32 v157, s38, v114
	s_addk_i32 s38, 0x4000
	v_mov_b64_e32 v[60:61], v[12:13]
	v_mov_b64_e32 v[58:59], v[10:11]
	v_mov_b64_e32 v[56:57], v[8:9]
	v_mov_b64_e32 v[54:55], v[6:7]
	v_mov_b64_e32 v[52:53], v[4:5]
	v_mov_b64_e32 v[50:51], v[2:3]
	v_mov_b64_e32 v[48:49], v[0:1]
	v_mov_b64_e32 v[44:45], v[12:13]
	v_mov_b64_e32 v[42:43], v[10:11]
	v_mov_b64_e32 v[40:41], v[8:9]
	v_mov_b64_e32 v[38:39], v[6:7]
	v_mov_b64_e32 v[36:37], v[4:5]
	v_mov_b64_e32 v[34:35], v[2:3]
	v_mov_b64_e32 v[32:33], v[0:1]
	v_mov_b64_e32 v[28:29], v[12:13]
	v_mov_b64_e32 v[26:27], v[10:11]
	v_mov_b64_e32 v[24:25], v[8:9]
	v_mov_b64_e32 v[22:23], v[6:7]
	v_mov_b64_e32 v[20:21], v[4:5]
	v_mov_b64_e32 v[18:19], v[2:3]
	v_mov_b64_e32 v[16:17], v[0:1]
	v_add_u32_e32 v140, s38, v114
	v_pk_fma_f32 v[126:127], v[94:95], s[34:35], v[130:131] op_sel_hi:[1,0,0]
	v_pk_fma_f32 v[132:133], v[92:93], s[34:35], v[130:131] op_sel_hi:[1,0,0]
	v_pk_fma_f32 v[134:135], v[90:91], s[34:35], v[130:131] op_sel_hi:[1,0,0]
	v_pk_fma_f32 v[112:113], v[88:89], s[34:35], v[130:131] op_sel_hi:[1,0,0]
	v_pk_fma_f32 v[114:115], v[86:87], s[34:35], v[130:131] op_sel_hi:[1,0,0]
	v_pk_fma_f32 v[124:125], v[84:85], s[34:35], v[130:131] op_sel_hi:[1,0,0]
	v_pk_fma_f32 v[128:129], v[82:83], s[34:35], v[130:131] op_sel_hi:[1,0,0]
	v_pk_fma_f32 v[130:131], v[80:81], s[34:35], v[130:131] op_sel_hi:[1,0,0]
	v_cndmask_b32_e64 v179, v141, 1.0, vcc
	v_mov_b32_e32 v141, 0
	s_waitcnt vmcnt(2)
	ds_write_b128 v151, v[190:193] offset:16384
	ds_write_b128 v152, v[180:183] offset:16384
	s_waitcnt vmcnt(1)
	ds_write_b128 v148, v[214:217] offset:57344
	ds_write_b128 v149, v[186:189] offset:57344
	s_waitcnt vmcnt(0)
	ds_write_b128 v150, v[218:221] offset:57344
	s_waitcnt lgkmcnt(0)
	s_barrier
